# speedup vs baseline: 1.0182x; 1.0030x over previous
; __device__ __forceinline__ f32x4 mfma16(bf16x8 a, bf16x8 b, f32x4 c) { return __builtin_amdgcn_mfma_f32_16x16x32_bf16(a, b, c, 0, 0, 0); }
; template <int NT, bool LOWREG = false>
; __device__ __forceinline__ void gemm_mainloop(const bh* __restrict__ A, long lda, const bh* __restrict__ B, long ldb, int K,
;                                               char* lds, f32x4 (&acc)[4][NT]) {
;     ...
;     const char* sb = lds + (kt & 1) * STAGE;
;     const char* a_base = sb + (wr * 64 + fr) * LROW + fq * 16;
;     const char* b_base = sb + A_BYTES + (wc * (16 * NT) + fr) * LROW + fq * 16;
; #pragma unroll
;     for (int ks = 0; ks < 2; ++ks) {
;       if constexpr (LOWREG) {
;         bf16x8 bfr[NT];
; #pragma unroll
;         for (int n = 0; n < NT; ++n) bfr[n] = *reinterpret_cast<const bf16x8*>(b_base + n * 16 * LROW + ks * 64);
; #pragma unroll
;         for (int mp = 0; mp < 2; ++mp) {
;           bf16x8 af[2];
; #pragma unroll
;           for (int m = 0; m < 2; ++m) af[m] = *reinterpret_cast<const bf16x8*>(a_base + (mp * 2 + m) * 16 * LROW + ks * 64);
;           __builtin_amdgcn_s_setprio(1);
; #pragma unroll
;           for (int m = 0; m < 2; ++m)
; #pragma unroll
;             for (int n = 0; n < NT; ++n) acc[mp * 2 + m][n] = mfma16(af[m], bfr[n], acc[mp * 2 + m][n]);
;           __builtin_amdgcn_s_setprio(0);
;         }
;       } else {
;       bf16x8 af[4], bfr[NT];
; #pragma unroll
;       for (int m = 0; m < 4; ++m) af[m] = *reinterpret_cast<const bf16x8*>(a_base + m * 16 * LROW + ks * 64);
; #pragma unroll
;       for (int n = 0; n < NT; ++n) bfr[n] = *reinterpret_cast<const bf16x8*>(b_base + n * 16 * LROW + ks * 64);
;       __builtin_amdgcn_s_setprio(1);
; #pragma unroll
;       for (int m = 0; m < 4; ++m)
; #pragma unroll
;         for (int n = 0; n < NT; ++n) acc[m][n] = mfma16(af[m], bfr[n], acc[m][n]);
;       __builtin_amdgcn_s_setprio(0);
;       }
;     }
;     if (more) {
;       char* wb = lds + ((kt + 1) & 1) * STAGE;
; #pragma unroll
;       for (int i = 0; i < 4; ++i) *reinterpret_cast<bf16x8*>(wb + (srow + 64 * i) * LROW + scol * 2) = ra[i];
; #pragma unroll
;       for (int i = 0; i < NB; ++i) *reinterpret_cast<bf16x8*>(wb + A_BYTES + (srow + 64 * i) * LROW + scol * 2) = rb[i];
;     }
;     __syncthreads();
.LBB0_211:
	s_add_i32 s5, s3, 1
	s_bitcmp1_b32 s3, 0
	s_cselect_b32 s3, 0xc800, 0
	s_add_i32 s3, s3, 32
	v_add3_u32 v86, s3, v60, v58
	v_add3_u32 v87, s3, v61, v58
	ds_read_b128 v[62:65], v86
	ds_read_b128 v[66:69], v86 offset:2560
	ds_read_b128 v[70:73], v86 offset:5120
	ds_read_b128 v[74:77], v86 offset:7680
	ds_read_b128 v[78:81], v87 offset:40960
	ds_read_b128 v[82:85], v87 offset:43520
	s_setprio 1
	s_waitcnt lgkmcnt(1)
	v_mfma_f32_16x16x32_bf16 v[48:51], v[62:65], v[78:81], v[48:51]
	s_waitcnt lgkmcnt(0)
	v_mfma_f32_16x16x32_bf16 v[44:47], v[62:65], v[82:85], v[44:47]
	v_mfma_f32_16x16x32_bf16 v[40:43], v[66:69], v[78:81], v[40:43]
	v_mfma_f32_16x16x32_bf16 v[24:27], v[66:69], v[82:85], v[24:27]
	v_mfma_f32_16x16x32_bf16 v[12:15], v[70:73], v[78:81], v[12:15]
	v_mfma_f32_16x16x32_bf16 v[8:11], v[70:73], v[82:85], v[8:11]
	v_mfma_f32_16x16x32_bf16 v[4:7], v[74:77], v[78:81], v[4:7]
	v_mfma_f32_16x16x32_bf16 v[0:3], v[74:77], v[82:85], v[0:3]
	s_setprio 0
	ds_read_b128 v[62:65], v86 offset:64
	ds_read_b128 v[66:69], v86 offset:2624
	ds_read_b128 v[70:73], v86 offset:5184
	ds_read_b128 v[74:77], v86 offset:7744
	ds_read_b128 v[78:81], v87 offset:41024
	ds_read_b128 v[82:85], v87 offset:43584
	s_andn2_b64 vcc, exec, s[10:11]
	s_cbranch_vccnz .Lmy_il_last_208
	s_bitcmp1_b32 s5, 0
	s_cselect_b32 s3, 0xc800, 0
	s_add_i32 s3, s3, 32
	s_setprio 1
	s_waitcnt lgkmcnt(1)
	v_mfma_f32_16x16x32_bf16 v[48:51], v[62:65], v[78:81], v[48:51]
	s_waitcnt lgkmcnt(0)
	v_mfma_f32_16x16x32_bf16 v[44:47], v[62:65], v[82:85], v[44:47]
	v_mfma_f32_16x16x32_bf16 v[40:43], v[66:69], v[78:81], v[40:43]
	v_add3_u32 v62, s3, v176, v59
	s_waitcnt vmcnt(4)
	ds_write_b128 v62, v[16:19]
	v_mfma_f32_16x16x32_bf16 v[24:27], v[66:69], v[82:85], v[24:27]
	s_waitcnt vmcnt(3)
	ds_write_b128 v62, v[20:23] offset:10240
	v_mfma_f32_16x16x32_bf16 v[12:15], v[70:73], v[78:81], v[12:15]
	s_waitcnt vmcnt(2)
	ds_write_b128 v62, v[28:31] offset:20480
	v_mfma_f32_16x16x32_bf16 v[8:11], v[70:73], v[82:85], v[8:11]
	s_waitcnt vmcnt(1)
	ds_write_b128 v62, v[32:35] offset:30720
	v_mfma_f32_16x16x32_bf16 v[4:7], v[74:77], v[78:81], v[4:7]
	v_add3_u32 v62, s3, v59, v176
	s_waitcnt vmcnt(0)
	ds_write_b128 v62, v[36:39] offset:40960
	v_mfma_f32_16x16x32_bf16 v[0:3], v[74:77], v[82:85], v[0:3]
	s_setprio 0
	s_branch .LBB0_208
.Lmy_il_last_208:
	s_setprio 1
	s_waitcnt lgkmcnt(1)
	v_mfma_f32_16x16x32_bf16 v[48:51], v[62:65], v[78:81], v[48:51]
	s_waitcnt lgkmcnt(0)
	v_mfma_f32_16x16x32_bf16 v[44:47], v[62:65], v[82:85], v[44:47]
	v_mfma_f32_16x16x32_bf16 v[40:43], v[66:69], v[78:81], v[40:43]
	v_mfma_f32_16x16x32_bf16 v[24:27], v[66:69], v[82:85], v[24:27]
	v_mfma_f32_16x16x32_bf16 v[12:15], v[70:73], v[78:81], v[12:15]
	v_mfma_f32_16x16x32_bf16 v[8:11], v[70:73], v[82:85], v[8:11]
	v_mfma_f32_16x16x32_bf16 v[4:7], v[74:77], v[78:81], v[4:7]
	v_mfma_f32_16x16x32_bf16 v[0:3], v[74:77], v[82:85], v[0:3]
	s_setprio 0
	s_branch .LBB0_208

; __device__ __forceinline__ f32x4 mfma16(bf16x8 a, bf16x8 b, f32x4 c) { return __builtin_amdgcn_mfma_f32_16x16x32_bf16(a, b, c, 0, 0, 0); }
; template <int NT, bool LOWREG = false>
; __device__ __forceinline__ void gemm_mainloop(const bh* __restrict__ A, long lda, const bh* __restrict__ B, long ldb, int K,
;                                               char* lds, f32x4 (&acc)[4][NT]) {
;     ...
;     const char* sb = lds + (kt & 1) * STAGE;
;     const char* a_base = sb + (wr * 64 + fr) * LROW + fq * 16;
;     const char* b_base = sb + A_BYTES + (wc * (16 * NT) + fr) * LROW + fq * 16;
; #pragma unroll
;     for (int ks = 0; ks < 2; ++ks) {
;       if constexpr (LOWREG) {
;         bf16x8 bfr[NT];
; #pragma unroll
;         for (int n = 0; n < NT; ++n) bfr[n] = *reinterpret_cast<const bf16x8*>(b_base + n * 16 * LROW + ks * 64);
; #pragma unroll
;         for (int mp = 0; mp < 2; ++mp) {
;           bf16x8 af[2];
; #pragma unroll
;           for (int m = 0; m < 2; ++m) af[m] = *reinterpret_cast<const bf16x8*>(a_base + (mp * 2 + m) * 16 * LROW + ks * 64);
;           __builtin_amdgcn_s_setprio(1);
; #pragma unroll
;           for (int m = 0; m < 2; ++m)
; #pragma unroll
;             for (int n = 0; n < NT; ++n) acc[mp * 2 + m][n] = mfma16(af[m], bfr[n], acc[mp * 2 + m][n]);
;           __builtin_amdgcn_s_setprio(0);
;         }
;       } else {
;       bf16x8 af[4], bfr[NT];
; #pragma unroll
;       for (int m = 0; m < 4; ++m) af[m] = *reinterpret_cast<const bf16x8*>(a_base + m * 16 * LROW + ks * 64);
; #pragma unroll
;       for (int n = 0; n < NT; ++n) bfr[n] = *reinterpret_cast<const bf16x8*>(b_base + n * 16 * LROW + ks * 64);
;       __builtin_amdgcn_s_setprio(1);
; #pragma unroll
;       for (int m = 0; m < 4; ++m)
; #pragma unroll
;         for (int n = 0; n < NT; ++n) acc[m][n] = mfma16(af[m], bfr[n], acc[m][n]);
;       __builtin_amdgcn_s_setprio(0);
;       }
;     }
;     if (more) {
;       char* wb = lds + ((kt + 1) & 1) * STAGE;
; #pragma unroll
;       for (int i = 0; i < 4; ++i) *reinterpret_cast<bf16x8*>(wb + (srow + 64 * i) * LROW + scol * 2) = ra[i];
; #pragma unroll
;       for (int i = 0; i < NB; ++i) *reinterpret_cast<bf16x8*>(wb + A_BYTES + (srow + 64 * i) * LROW + scol * 2) = rb[i];
;     }
;     __syncthreads();
.LBB0_373:
	s_add_i32 s12, s3, 1
	s_bitcmp1_b32 s3, 0
	s_cselect_b32 s3, 0xf000, 0
	s_add_i32 s3, s3, 32
	v_add3_u32 v130, s3, v97, v94
	v_add3_u32 v131, s3, v95, v94
	ds_read_b128 v[98:101], v130
	ds_read_b128 v[102:105], v130 offset:2560
	ds_read_b128 v[106:109], v130 offset:5120
	ds_read_b128 v[110:113], v130 offset:7680
	ds_read_b128 v[114:117], v131 offset:40960
	ds_read_b128 v[118:121], v131 offset:43520
	ds_read_b128 v[122:125], v131 offset:46080
	ds_read_b128 v[126:129], v131 offset:48640
	s_setprio 1
	s_waitcnt lgkmcnt(3)
	v_mfma_f32_16x16x32_bf16 v[84:87], v[98:101], v[114:117], v[84:87]
	s_waitcnt lgkmcnt(2)
	v_mfma_f32_16x16x32_bf16 v[80:83], v[98:101], v[118:121], v[80:83]
	s_waitcnt lgkmcnt(1)
	v_mfma_f32_16x16x32_bf16 v[76:79], v[98:101], v[122:125], v[76:79]
	s_waitcnt lgkmcnt(0)
	v_mfma_f32_16x16x32_bf16 v[72:75], v[98:101], v[126:129], v[72:75]
	v_mfma_f32_16x16x32_bf16 v[68:71], v[102:105], v[114:117], v[68:71]
	v_mfma_f32_16x16x32_bf16 v[64:67], v[102:105], v[118:121], v[64:67]
	v_mfma_f32_16x16x32_bf16 v[60:63], v[102:105], v[122:125], v[60:63]
	v_mfma_f32_16x16x32_bf16 v[52:55], v[102:105], v[126:129], v[52:55]
	v_mfma_f32_16x16x32_bf16 v[36:39], v[106:109], v[114:117], v[36:39]
	v_mfma_f32_16x16x32_bf16 v[24:27], v[106:109], v[118:121], v[24:27]
	v_mfma_f32_16x16x32_bf16 v[20:23], v[106:109], v[122:125], v[20:23]
	v_mfma_f32_16x16x32_bf16 v[16:19], v[106:109], v[126:129], v[16:19]
	v_mfma_f32_16x16x32_bf16 v[12:15], v[110:113], v[114:117], v[12:15]
	v_mfma_f32_16x16x32_bf16 v[8:11], v[110:113], v[118:121], v[8:11]
	v_mfma_f32_16x16x32_bf16 v[4:7], v[110:113], v[122:125], v[4:7]
	v_mfma_f32_16x16x32_bf16 v[0:3], v[110:113], v[126:129], v[0:3]
	s_setprio 0
	ds_read_b128 v[98:101], v130 offset:64
	ds_read_b128 v[102:105], v130 offset:2624
	ds_read_b128 v[106:109], v130 offset:5184
	ds_read_b128 v[110:113], v130 offset:7744
	ds_read_b128 v[114:117], v131 offset:41024
	ds_read_b128 v[118:121], v131 offset:43584
	ds_read_b128 v[122:125], v131 offset:46144
	ds_read_b128 v[126:129], v131 offset:48704
	s_andn2_b64 vcc, exec, s[6:7]
	s_cbranch_vccnz .Lmy_il_last_370
	s_bitcmp1_b32 s12, 0
	s_cselect_b32 s3, 0xf000, 0
	s_setprio 1
	s_waitcnt lgkmcnt(3)
	v_mfma_f32_16x16x32_bf16 v[84:87], v[98:101], v[114:117], v[84:87]
	s_waitcnt lgkmcnt(2)
	v_mfma_f32_16x16x32_bf16 v[80:83], v[98:101], v[118:121], v[80:83]
	s_waitcnt lgkmcnt(1)
	v_mfma_f32_16x16x32_bf16 v[76:79], v[98:101], v[122:125], v[76:79]
	s_waitcnt lgkmcnt(0)
	v_mfma_f32_16x16x32_bf16 v[72:75], v[98:101], v[126:129], v[72:75]
	v_mfma_f32_16x16x32_bf16 v[68:71], v[102:105], v[114:117], v[68:71]
	v_add_u32_e32 v98, s3, v96
	s_waitcnt vmcnt(5)
	ds_write_b128 v98, v[28:31]
	v_mfma_f32_16x16x32_bf16 v[64:67], v[102:105], v[118:121], v[64:67]
	v_mfma_f32_16x16x32_bf16 v[60:63], v[102:105], v[122:125], v[60:63]
	s_waitcnt vmcnt(4)
	ds_write_b128 v98, v[32:35] offset:10240
	v_mfma_f32_16x16x32_bf16 v[52:55], v[102:105], v[126:129], v[52:55]
	v_mfma_f32_16x16x32_bf16 v[36:39], v[106:109], v[114:117], v[36:39]
	s_waitcnt vmcnt(3)
	ds_write_b128 v98, v[40:43] offset:20480
	v_mfma_f32_16x16x32_bf16 v[24:27], v[106:109], v[118:121], v[24:27]
	v_mfma_f32_16x16x32_bf16 v[20:23], v[106:109], v[122:125], v[20:23]
	s_waitcnt vmcnt(2)
	ds_write_b128 v98, v[44:47] offset:30720
	v_mfma_f32_16x16x32_bf16 v[16:19], v[106:109], v[126:129], v[16:19]
	v_mfma_f32_16x16x32_bf16 v[12:15], v[110:113], v[114:117], v[12:15]
	s_waitcnt vmcnt(1)
	ds_write_b128 v98, v[48:51] offset:40960
	v_mfma_f32_16x16x32_bf16 v[8:11], v[110:113], v[118:121], v[8:11]
	v_mfma_f32_16x16x32_bf16 v[4:7], v[110:113], v[122:125], v[4:7]
	s_waitcnt vmcnt(0)
	ds_write_b128 v98, v[56:59] offset:51200
	v_mfma_f32_16x16x32_bf16 v[0:3], v[110:113], v[126:129], v[0:3]
	s_setprio 0
	s_branch .LBB0_370
.Lmy_il_last_370:
	s_setprio 1
	s_waitcnt lgkmcnt(3)
	v_mfma_f32_16x16x32_bf16 v[84:87], v[98:101], v[114:117], v[84:87]
	s_waitcnt lgkmcnt(2)
	v_mfma_f32_16x16x32_bf16 v[80:83], v[98:101], v[118:121], v[80:83]
	s_waitcnt lgkmcnt(1)
	v_mfma_f32_16x16x32_bf16 v[76:79], v[98:101], v[122:125], v[76:79]
	s_waitcnt lgkmcnt(0)
	v_mfma_f32_16x16x32_bf16 v[72:75], v[98:101], v[126:129], v[72:75]
	v_mfma_f32_16x16x32_bf16 v[68:71], v[102:105], v[114:117], v[68:71]
	v_mfma_f32_16x16x32_bf16 v[64:67], v[102:105], v[118:121], v[64:67]
	v_mfma_f32_16x16x32_bf16 v[60:63], v[102:105], v[122:125], v[60:63]
	v_mfma_f32_16x16x32_bf16 v[52:55], v[102:105], v[126:129], v[52:55]
	v_mfma_f32_16x16x32_bf16 v[36:39], v[106:109], v[114:117], v[36:39]
	v_mfma_f32_16x16x32_bf16 v[24:27], v[106:109], v[118:121], v[24:27]
	v_mfma_f32_16x16x32_bf16 v[20:23], v[106:109], v[122:125], v[20:23]
	v_mfma_f32_16x16x32_bf16 v[16:19], v[106:109], v[126:129], v[16:19]
	v_mfma_f32_16x16x32_bf16 v[12:15], v[110:113], v[114:117], v[12:15]
	v_mfma_f32_16x16x32_bf16 v[8:11], v[110:113], v[118:121], v[8:11]
	v_mfma_f32_16x16x32_bf16 v[4:7], v[110:113], v[122:125], v[4:7]
	v_mfma_f32_16x16x32_bf16 v[0:3], v[110:113], v[126:129], v[0:3]
	s_setprio 0
	s_branch .LBB0_370

; __device__ __forceinline__ f32x4 mfma16(bf16x8 a, bf16x8 b, f32x4 c) { return __builtin_amdgcn_mfma_f32_16x16x32_bf16(a, b, c, 0, 0, 0); }
; template <int NT, bool LOWREG = false>
; __device__ __forceinline__ void gemm_mainloop(const bh* __restrict__ A, long lda, const bh* __restrict__ B, long ldb, int K,
;                                               char* lds, f32x4 (&acc)[4][NT]) {
;     ...
;     const char* sb = lds + (kt & 1) * STAGE;
;     const char* a_base = sb + (wr * 64 + fr) * LROW + fq * 16;
;     const char* b_base = sb + A_BYTES + (wc * (16 * NT) + fr) * LROW + fq * 16;
; #pragma unroll
;     for (int ks = 0; ks < 2; ++ks) {
;       if constexpr (LOWREG) {
;         bf16x8 bfr[NT];
; #pragma unroll
;         for (int n = 0; n < NT; ++n) bfr[n] = *reinterpret_cast<const bf16x8*>(b_base + n * 16 * LROW + ks * 64);
; #pragma unroll
;         for (int mp = 0; mp < 2; ++mp) {
;           bf16x8 af[2];
; #pragma unroll
;           for (int m = 0; m < 2; ++m) af[m] = *reinterpret_cast<const bf16x8*>(a_base + (mp * 2 + m) * 16 * LROW + ks * 64);
;           __builtin_amdgcn_s_setprio(1);
; #pragma unroll
;           for (int m = 0; m < 2; ++m)
; #pragma unroll
;             for (int n = 0; n < NT; ++n) acc[mp * 2 + m][n] = mfma16(af[m], bfr[n], acc[mp * 2 + m][n]);
;           __builtin_amdgcn_s_setprio(0);
;         }
;       } else {
;       bf16x8 af[4], bfr[NT];
; #pragma unroll
;       for (int m = 0; m < 4; ++m) af[m] = *reinterpret_cast<const bf16x8*>(a_base + m * 16 * LROW + ks * 64);
; #pragma unroll
;       for (int n = 0; n < NT; ++n) bfr[n] = *reinterpret_cast<const bf16x8*>(b_base + n * 16 * LROW + ks * 64);
;       __builtin_amdgcn_s_setprio(1);
; #pragma unroll
;       for (int m = 0; m < 4; ++m)
; #pragma unroll
;         for (int n = 0; n < NT; ++n) acc[m][n] = mfma16(af[m], bfr[n], acc[m][n]);
;       __builtin_amdgcn_s_setprio(0);
;       }
;     }
;     if (more) {
;       char* wb = lds + ((kt + 1) & 1) * STAGE;
; #pragma unroll
;       for (int i = 0; i < 4; ++i) *reinterpret_cast<bf16x8*>(wb + (srow + 64 * i) * LROW + scol * 2) = ra[i];
; #pragma unroll
;       for (int i = 0; i < NB; ++i) *reinterpret_cast<bf16x8*>(wb + A_BYTES + (srow + 64 * i) * LROW + scol * 2) = rb[i];
;     }
;     __syncthreads();
.LBB0_384:
	s_add_i32 s12, s3, 1
	s_bitcmp1_b32 s3, 0
	s_cselect_b32 s3, 0xf000, 0
	s_add_i32 s3, s3, 32
	v_add3_u32 v97, s3, v96, v93
	v_add3_u32 v130, s3, v94, v93
	ds_read_b128 v[98:101], v97
	ds_read_b128 v[102:105], v97 offset:2560
	ds_read_b128 v[106:109], v97 offset:5120
	ds_read_b128 v[110:113], v97 offset:7680
	ds_read_b128 v[114:117], v130 offset:40960
	ds_read_b128 v[118:121], v130 offset:43520
	ds_read_b128 v[122:125], v130 offset:46080
	ds_read_b128 v[126:129], v130 offset:48640
	s_setprio 1
	s_waitcnt lgkmcnt(3)
	v_mfma_f32_16x16x32_bf16 v[84:87], v[98:101], v[114:117], v[84:87]
	s_waitcnt lgkmcnt(2)
	v_mfma_f32_16x16x32_bf16 v[80:83], v[98:101], v[118:121], v[80:83]
	s_waitcnt lgkmcnt(1)
	v_mfma_f32_16x16x32_bf16 v[76:79], v[98:101], v[122:125], v[76:79]
	s_waitcnt lgkmcnt(0)
	v_mfma_f32_16x16x32_bf16 v[72:75], v[98:101], v[126:129], v[72:75]
	v_mfma_f32_16x16x32_bf16 v[68:71], v[102:105], v[114:117], v[68:71]
	v_mfma_f32_16x16x32_bf16 v[64:67], v[102:105], v[118:121], v[64:67]
	v_mfma_f32_16x16x32_bf16 v[60:63], v[102:105], v[122:125], v[60:63]
	v_mfma_f32_16x16x32_bf16 v[56:59], v[102:105], v[126:129], v[56:59]
	v_mfma_f32_16x16x32_bf16 v[52:55], v[106:109], v[114:117], v[52:55]
	v_mfma_f32_16x16x32_bf16 v[48:51], v[106:109], v[118:121], v[48:51]
	v_mfma_f32_16x16x32_bf16 v[40:43], v[106:109], v[122:125], v[40:43]
	v_mfma_f32_16x16x32_bf16 v[32:35], v[106:109], v[126:129], v[32:35]
	v_mfma_f32_16x16x32_bf16 v[12:15], v[110:113], v[114:117], v[12:15]
	v_mfma_f32_16x16x32_bf16 v[8:11], v[110:113], v[118:121], v[8:11]
	v_mfma_f32_16x16x32_bf16 v[4:7], v[110:113], v[122:125], v[4:7]
	v_mfma_f32_16x16x32_bf16 v[0:3], v[110:113], v[126:129], v[0:3]
	s_setprio 0
	ds_read_b128 v[98:101], v97 offset:64
	ds_read_b128 v[102:105], v97 offset:2624
	ds_read_b128 v[106:109], v97 offset:5184
	ds_read_b128 v[110:113], v97 offset:7744
	ds_read_b128 v[114:117], v130 offset:41024
	ds_read_b128 v[118:121], v130 offset:43584
	ds_read_b128 v[122:125], v130 offset:46144
	ds_read_b128 v[126:129], v130 offset:48704
	s_andn2_b64 vcc, exec, s[6:7]
	s_cbranch_vccnz .Lmy_il_last_381
	s_bitcmp1_b32 s12, 0
	s_cselect_b32 s3, 0xf000, 0
	s_setprio 1
	s_waitcnt lgkmcnt(3)
	v_mfma_f32_16x16x32_bf16 v[84:87], v[98:101], v[114:117], v[84:87]
	s_waitcnt lgkmcnt(2)
	v_mfma_f32_16x16x32_bf16 v[80:83], v[98:101], v[118:121], v[80:83]
	s_waitcnt lgkmcnt(1)
	v_mfma_f32_16x16x32_bf16 v[76:79], v[98:101], v[122:125], v[76:79]
	s_waitcnt lgkmcnt(0)
	v_mfma_f32_16x16x32_bf16 v[72:75], v[98:101], v[126:129], v[72:75]
	v_mfma_f32_16x16x32_bf16 v[68:71], v[102:105], v[114:117], v[68:71]
	v_add_u32_e32 v97, s3, v95
	s_waitcnt vmcnt(5)
	ds_write_b128 v97, v[16:19]
	v_mfma_f32_16x16x32_bf16 v[64:67], v[102:105], v[118:121], v[64:67]
	v_mfma_f32_16x16x32_bf16 v[60:63], v[102:105], v[122:125], v[60:63]
	s_waitcnt vmcnt(4)
	ds_write_b128 v97, v[20:23] offset:10240
	v_mfma_f32_16x16x32_bf16 v[56:59], v[102:105], v[126:129], v[56:59]
	v_mfma_f32_16x16x32_bf16 v[52:55], v[106:109], v[114:117], v[52:55]
	s_waitcnt vmcnt(3)
	ds_write_b128 v97, v[24:27] offset:20480
	v_mfma_f32_16x16x32_bf16 v[48:51], v[106:109], v[118:121], v[48:51]
	v_mfma_f32_16x16x32_bf16 v[40:43], v[106:109], v[122:125], v[40:43]
	s_waitcnt vmcnt(2)
	ds_write_b128 v97, v[28:31] offset:30720
	v_mfma_f32_16x16x32_bf16 v[32:35], v[106:109], v[126:129], v[32:35]
	v_mfma_f32_16x16x32_bf16 v[12:15], v[110:113], v[114:117], v[12:15]
	s_waitcnt vmcnt(1)
	ds_write_b128 v97, v[36:39] offset:40960
	v_mfma_f32_16x16x32_bf16 v[8:11], v[110:113], v[118:121], v[8:11]
	v_mfma_f32_16x16x32_bf16 v[4:7], v[110:113], v[122:125], v[4:7]
	s_waitcnt vmcnt(0)
	ds_write_b128 v97, v[44:47] offset:51200
	v_mfma_f32_16x16x32_bf16 v[0:3], v[110:113], v[126:129], v[0:3]
	s_setprio 0
	s_branch .LBB0_381
.Lmy_il_last_381:
	s_setprio 1
	s_waitcnt lgkmcnt(3)
	v_mfma_f32_16x16x32_bf16 v[84:87], v[98:101], v[114:117], v[84:87]
	s_waitcnt lgkmcnt(2)
	v_mfma_f32_16x16x32_bf16 v[80:83], v[98:101], v[118:121], v[80:83]
	s_waitcnt lgkmcnt(1)
	v_mfma_f32_16x16x32_bf16 v[76:79], v[98:101], v[122:125], v[76:79]
	s_waitcnt lgkmcnt(0)
	v_mfma_f32_16x16x32_bf16 v[72:75], v[98:101], v[126:129], v[72:75]
	v_mfma_f32_16x16x32_bf16 v[68:71], v[102:105], v[114:117], v[68:71]
	v_mfma_f32_16x16x32_bf16 v[64:67], v[102:105], v[118:121], v[64:67]
	v_mfma_f32_16x16x32_bf16 v[60:63], v[102:105], v[122:125], v[60:63]
	v_mfma_f32_16x16x32_bf16 v[56:59], v[102:105], v[126:129], v[56:59]
	v_mfma_f32_16x16x32_bf16 v[52:55], v[106:109], v[114:117], v[52:55]
	v_mfma_f32_16x16x32_bf16 v[48:51], v[106:109], v[118:121], v[48:51]
	v_mfma_f32_16x16x32_bf16 v[40:43], v[106:109], v[122:125], v[40:43]
	v_mfma_f32_16x16x32_bf16 v[32:35], v[106:109], v[126:129], v[32:35]
	v_mfma_f32_16x16x32_bf16 v[12:15], v[110:113], v[114:117], v[12:15]
	v_mfma_f32_16x16x32_bf16 v[8:11], v[110:113], v[118:121], v[8:11]
	v_mfma_f32_16x16x32_bf16 v[4:7], v[110:113], v[122:125], v[4:7]
	v_mfma_f32_16x16x32_bf16 v[0:3], v[110:113], v[126:129], v[0:3]
	s_setprio 0
	s_branch .LBB0_381

; __device__ __forceinline__ f32x4 mfma16(bf16x8 a, bf16x8 b, f32x4 c) { return __builtin_amdgcn_mfma_f32_16x16x32_bf16(a, b, c, 0, 0, 0); }
; template <int NT, bool LOWREG = false>
; __device__ __forceinline__ void gemm_mainloop(const bh* __restrict__ A, long lda, const bh* __restrict__ B, long ldb, int K,
;                                               char* lds, f32x4 (&acc)[4][NT]) {
;     ...
;     const char* sb = lds + (kt & 1) * STAGE;
;     const char* a_base = sb + (wr * 64 + fr) * LROW + fq * 16;
;     const char* b_base = sb + A_BYTES + (wc * (16 * NT) + fr) * LROW + fq * 16;
; #pragma unroll
;     for (int ks = 0; ks < 2; ++ks) {
;       if constexpr (LOWREG) {
;         bf16x8 bfr[NT];
; #pragma unroll
;         for (int n = 0; n < NT; ++n) bfr[n] = *reinterpret_cast<const bf16x8*>(b_base + n * 16 * LROW + ks * 64);
; #pragma unroll
;         for (int mp = 0; mp < 2; ++mp) {
;           bf16x8 af[2];
; #pragma unroll
;           for (int m = 0; m < 2; ++m) af[m] = *reinterpret_cast<const bf16x8*>(a_base + (mp * 2 + m) * 16 * LROW + ks * 64);
;           __builtin_amdgcn_s_setprio(1);
; #pragma unroll
;           for (int m = 0; m < 2; ++m)
; #pragma unroll
;             for (int n = 0; n < NT; ++n) acc[mp * 2 + m][n] = mfma16(af[m], bfr[n], acc[mp * 2 + m][n]);
;           __builtin_amdgcn_s_setprio(0);
;         }
;       } else {
;       bf16x8 af[4], bfr[NT];
; #pragma unroll
;       for (int m = 0; m < 4; ++m) af[m] = *reinterpret_cast<const bf16x8*>(a_base + m * 16 * LROW + ks * 64);
; #pragma unroll
;       for (int n = 0; n < NT; ++n) bfr[n] = *reinterpret_cast<const bf16x8*>(b_base + n * 16 * LROW + ks * 64);
;       __builtin_amdgcn_s_setprio(1);
; #pragma unroll
;       for (int m = 0; m < 4; ++m)
; #pragma unroll
;         for (int n = 0; n < NT; ++n) acc[m][n] = mfma16(af[m], bfr[n], acc[m][n]);
;       __builtin_amdgcn_s_setprio(0);
;       }
;     }
;     if (more) {
;       char* wb = lds + ((kt + 1) & 1) * STAGE;
; #pragma unroll
;       for (int i = 0; i < 4; ++i) *reinterpret_cast<bf16x8*>(wb + (srow + 64 * i) * LROW + scol * 2) = ra[i];
; #pragma unroll
;       for (int i = 0; i < NB; ++i) *reinterpret_cast<bf16x8*>(wb + A_BYTES + (srow + 64 * i) * LROW + scol * 2) = rb[i];
;     }
;     __syncthreads();
.LBB0_455:
	s_add_i32 s3, s1, 1
	s_bitcmp1_b32 s1, 0
	s_cselect_b32 s1, 0xf000, 0
	s_add_i32 s1, s1, 32
	v_add3_u32 v97, s1, v95, v93
	v_add3_u32 v130, s1, v96, v93
	ds_read_b128 v[98:101], v97
	ds_read_b128 v[102:105], v97 offset:2560
	ds_read_b128 v[106:109], v97 offset:5120
	ds_read_b128 v[110:113], v97 offset:7680
	ds_read_b128 v[114:117], v130 offset:40960
	ds_read_b128 v[118:121], v130 offset:43520
	ds_read_b128 v[122:125], v130 offset:46080
	ds_read_b128 v[126:129], v130 offset:48640
	s_setprio 1
	s_waitcnt lgkmcnt(3)
	v_mfma_f32_16x16x32_bf16 v[84:87], v[98:101], v[114:117], v[84:87]
	s_waitcnt lgkmcnt(2)
	v_mfma_f32_16x16x32_bf16 v[80:83], v[98:101], v[118:121], v[80:83]
	s_waitcnt lgkmcnt(1)
	v_mfma_f32_16x16x32_bf16 v[76:79], v[98:101], v[122:125], v[76:79]
	s_waitcnt lgkmcnt(0)
	v_mfma_f32_16x16x32_bf16 v[72:75], v[98:101], v[126:129], v[72:75]
	v_mfma_f32_16x16x32_bf16 v[68:71], v[102:105], v[114:117], v[68:71]
	v_mfma_f32_16x16x32_bf16 v[64:67], v[102:105], v[118:121], v[64:67]
	v_mfma_f32_16x16x32_bf16 v[60:63], v[102:105], v[122:125], v[60:63]
	v_mfma_f32_16x16x32_bf16 v[56:59], v[102:105], v[126:129], v[56:59]
	v_mfma_f32_16x16x32_bf16 v[52:55], v[106:109], v[114:117], v[52:55]
	v_mfma_f32_16x16x32_bf16 v[48:51], v[106:109], v[118:121], v[48:51]
	v_mfma_f32_16x16x32_bf16 v[44:47], v[106:109], v[122:125], v[44:47]
	v_mfma_f32_16x16x32_bf16 v[40:43], v[106:109], v[126:129], v[40:43]
	v_mfma_f32_16x16x32_bf16 v[36:39], v[110:113], v[114:117], v[36:39]
	v_mfma_f32_16x16x32_bf16 v[28:31], v[110:113], v[118:121], v[28:31]
	v_mfma_f32_16x16x32_bf16 v[20:23], v[110:113], v[122:125], v[20:23]
	v_mfma_f32_16x16x32_bf16 v[8:11], v[110:113], v[126:129], v[8:11]
	s_setprio 0
	ds_read_b128 v[98:101], v97 offset:64
	ds_read_b128 v[102:105], v97 offset:2624
	ds_read_b128 v[106:109], v97 offset:5184
	ds_read_b128 v[110:113], v97 offset:7744
	ds_read_b128 v[114:117], v130 offset:41024
	ds_read_b128 v[118:121], v130 offset:43584
	ds_read_b128 v[122:125], v130 offset:46144
	ds_read_b128 v[126:129], v130 offset:48704
	s_andn2_b64 vcc, exec, s[18:19]
	s_cbranch_vccnz .Lmy_il_last_452
	s_bitcmp1_b32 s3, 0
	s_cselect_b32 s1, 0xf000, 0
	s_setprio 1
	s_waitcnt lgkmcnt(3)
	v_mfma_f32_16x16x32_bf16 v[84:87], v[98:101], v[114:117], v[84:87]
	s_waitcnt lgkmcnt(2)
	v_mfma_f32_16x16x32_bf16 v[80:83], v[98:101], v[118:121], v[80:83]
	s_waitcnt lgkmcnt(1)
	v_mfma_f32_16x16x32_bf16 v[76:79], v[98:101], v[122:125], v[76:79]
	s_waitcnt lgkmcnt(0)
	v_mfma_f32_16x16x32_bf16 v[72:75], v[98:101], v[126:129], v[72:75]
	v_mfma_f32_16x16x32_bf16 v[68:71], v[102:105], v[114:117], v[68:71]
	v_add_u32_e32 v97, s1, v94
	s_waitcnt vmcnt(5)
	ds_write_b128 v97, v[0:3]
	v_mfma_f32_16x16x32_bf16 v[64:67], v[102:105], v[118:121], v[64:67]
	v_mfma_f32_16x16x32_bf16 v[60:63], v[102:105], v[122:125], v[60:63]
	s_waitcnt vmcnt(4)
	ds_write_b128 v97, v[4:7] offset:10240
	v_mfma_f32_16x16x32_bf16 v[56:59], v[102:105], v[126:129], v[56:59]
	v_mfma_f32_16x16x32_bf16 v[52:55], v[106:109], v[114:117], v[52:55]
	s_waitcnt vmcnt(3)
	ds_write_b128 v97, v[12:15] offset:20480
	v_mfma_f32_16x16x32_bf16 v[48:51], v[106:109], v[118:121], v[48:51]
	v_mfma_f32_16x16x32_bf16 v[44:47], v[106:109], v[122:125], v[44:47]
	s_waitcnt vmcnt(2)
	ds_write_b128 v97, v[16:19] offset:30720
	v_mfma_f32_16x16x32_bf16 v[40:43], v[106:109], v[126:129], v[40:43]
	v_mfma_f32_16x16x32_bf16 v[36:39], v[110:113], v[114:117], v[36:39]
	s_waitcnt vmcnt(1)
	ds_write_b128 v97, v[24:27] offset:40960
	v_mfma_f32_16x16x32_bf16 v[28:31], v[110:113], v[118:121], v[28:31]
	v_mfma_f32_16x16x32_bf16 v[20:23], v[110:113], v[122:125], v[20:23]
	s_waitcnt vmcnt(0)
	ds_write_b128 v97, v[32:35] offset:51200
	v_mfma_f32_16x16x32_bf16 v[8:11], v[110:113], v[126:129], v[8:11]
	s_setprio 0
	s_branch .LBB0_452
.Lmy_il_last_452:
	s_setprio 1
	s_waitcnt lgkmcnt(3)
	v_mfma_f32_16x16x32_bf16 v[84:87], v[98:101], v[114:117], v[84:87]
	s_waitcnt lgkmcnt(2)
	v_mfma_f32_16x16x32_bf16 v[80:83], v[98:101], v[118:121], v[80:83]
	s_waitcnt lgkmcnt(1)
	v_mfma_f32_16x16x32_bf16 v[76:79], v[98:101], v[122:125], v[76:79]
	s_waitcnt lgkmcnt(0)
	v_mfma_f32_16x16x32_bf16 v[72:75], v[98:101], v[126:129], v[72:75]
	v_mfma_f32_16x16x32_bf16 v[68:71], v[102:105], v[114:117], v[68:71]
	v_mfma_f32_16x16x32_bf16 v[64:67], v[102:105], v[118:121], v[64:67]
	v_mfma_f32_16x16x32_bf16 v[60:63], v[102:105], v[122:125], v[60:63]
	v_mfma_f32_16x16x32_bf16 v[56:59], v[102:105], v[126:129], v[56:59]
	v_mfma_f32_16x16x32_bf16 v[52:55], v[106:109], v[114:117], v[52:55]
	v_mfma_f32_16x16x32_bf16 v[48:51], v[106:109], v[118:121], v[48:51]
	v_mfma_f32_16x16x32_bf16 v[44:47], v[106:109], v[122:125], v[44:47]
	v_mfma_f32_16x16x32_bf16 v[40:43], v[106:109], v[126:129], v[40:43]
	v_mfma_f32_16x16x32_bf16 v[36:39], v[110:113], v[114:117], v[36:39]
	v_mfma_f32_16x16x32_bf16 v[28:31], v[110:113], v[118:121], v[28:31]
	v_mfma_f32_16x16x32_bf16 v[20:23], v[110:113], v[122:125], v[20:23]
	v_mfma_f32_16x16x32_bf16 v[8:11], v[110:113], v[126:129], v[8:11]
	s_setprio 0
	s_branch .LBB0_452

; __device__ __forceinline__ f32x4 mfma16(bf16x8 a, bf16x8 b, f32x4 c) { return __builtin_amdgcn_mfma_f32_16x16x32_bf16(a, b, c, 0, 0, 0); }
; template <int NT, bool LOWREG = false>
; __device__ __forceinline__ void gemm_mainloop(const bh* __restrict__ A, long lda, const bh* __restrict__ B, long ldb, int K,
;                                               char* lds, f32x4 (&acc)[4][NT]) {
;     ...
;     for (int ks = 0; ks < 2; ++ks) {
;       if constexpr (LOWREG) {
;         bf16x8 bfr[NT];
; #pragma unroll
;         for (int n = 0; n < NT; ++n) bfr[n] = *reinterpret_cast<const bf16x8*>(b_base + n * 16 * LROW + ks * 64);
; #pragma unroll
;         for (int mp = 0; mp < 2; ++mp) {
;           bf16x8 af[2];
; #pragma unroll
;           for (int m = 0; m < 2; ++m) af[m] = *reinterpret_cast<const bf16x8*>(a_base + (mp * 2 + m) * 16 * LROW + ks * 64);
;           __builtin_amdgcn_s_setprio(1);
; #pragma unroll
;           for (int m = 0; m < 2; ++m)
; #pragma unroll
;             for (int n = 0; n < NT; ++n) acc[mp * 2 + m][n] = mfma16(af[m], bfr[n], acc[mp * 2 + m][n]);
;           __builtin_amdgcn_s_setprio(0);
;         }
;       } else {
;       bf16x8 af[4], bfr[NT];
; #pragma unroll
;       for (int m = 0; m < 4; ++m) af[m] = *reinterpret_cast<const bf16x8*>(a_base + m * 16 * LROW + ks * 64);
; #pragma unroll
;       for (int n = 0; n < NT; ++n) bfr[n] = *reinterpret_cast<const bf16x8*>(b_base + n * 16 * LROW + ks * 64);
;       __builtin_amdgcn_s_setprio(1);
; #pragma unroll
;       for (int m = 0; m < 4; ++m)
; #pragma unroll
;         for (int n = 0; n < NT; ++n) acc[m][n] = mfma16(af[m], bfr[n], acc[m][n]);
;       __builtin_amdgcn_s_setprio(0);
;       }
;     }
;     if (more) {
;       char* wb = lds + ((kt + 1) & 1) * STAGE;
; #pragma unroll
;       for (int i = 0; i < 4; ++i) *reinterpret_cast<bf16x8*>(wb + (srow + 64 * i) * LROW + scol * 2) = ra[i];
; #pragma unroll
;       for (int i = 0; i < NB; ++i) *reinterpret_cast<bf16x8*>(wb + A_BYTES + (srow + 64 * i) * LROW + scol * 2) = rb[i];
;     }
;     __syncthreads();
.LBB0_798:
	s_add_i32 s22, s21, 1
	s_bitcmp1_b32 s21, 0
	s_cselect_b32 s21, 0xf000, 0
	s_add_i32 s21, s21, 32
	v_add3_u32 v227, s21, v224, v223
	v_add3_u32 v176, s21, v226, v223
	ds_read_b128 v[198:201], v227 offset:40960
	ds_read_b128 v[228:231], v227 offset:43520
	ds_read_b128 v[232:235], v227 offset:46080
	ds_read_b128 v[236:239], v227 offset:48640
	ds_read_b128 v[240:243], v176
	ds_read_b128 v[244:247], v176 offset:2560
	s_setprio 1
	s_waitcnt lgkmcnt(1)
	v_mfma_f32_16x16x32_bf16 v[60:63], v[240:243], v[198:201], v[60:63]
	v_mfma_f32_16x16x32_bf16 v[52:55], v[240:243], v[228:231], v[52:55]
	v_mfma_f32_16x16x32_bf16 v[48:51], v[240:243], v[232:235], v[48:51]
	v_mfma_f32_16x16x32_bf16 v[56:59], v[240:243], v[236:239], v[56:59]
	s_waitcnt lgkmcnt(0)
	v_mfma_f32_16x16x32_bf16 v[40:43], v[244:247], v[198:201], v[40:43]
	v_mfma_f32_16x16x32_bf16 v[36:39], v[244:247], v[228:231], v[36:39]
	v_mfma_f32_16x16x32_bf16 v[32:35], v[244:247], v[232:235], v[32:35]
	v_mfma_f32_16x16x32_bf16 v[44:47], v[244:247], v[236:239], v[44:47]
	s_setprio 0
	ds_read_b128 v[240:243], v176 offset:5120
	ds_read_b128 v[244:247], v176 offset:7680
	s_setprio 1
	s_waitcnt lgkmcnt(1)
	v_mfma_f32_16x16x32_bf16 v[28:31], v[240:243], v[198:201], v[28:31]
	v_mfma_f32_16x16x32_bf16 v[20:23], v[240:243], v[228:231], v[20:23]
	v_mfma_f32_16x16x32_bf16 v[16:19], v[240:243], v[232:235], v[16:19]
	v_mfma_f32_16x16x32_bf16 v[24:27], v[240:243], v[236:239], v[24:27]
	s_waitcnt lgkmcnt(0)
	v_mfma_f32_16x16x32_bf16 v[8:11], v[244:247], v[198:201], v[8:11]
	v_mfma_f32_16x16x32_bf16 v[4:7], v[244:247], v[228:231], v[4:7]
	v_mfma_f32_16x16x32_bf16 v[0:3], v[244:247], v[232:235], v[0:3]
	v_mfma_f32_16x16x32_bf16 v[12:15], v[244:247], v[236:239], v[12:15]
	s_setprio 0
	ds_read_b128 v[198:201], v227 offset:41024
	ds_read_b128 v[228:231], v227 offset:43584
	ds_read_b128 v[232:235], v227 offset:46144
	ds_read_b128 v[236:239], v227 offset:48704
	ds_read_b128 v[240:243], v176 offset:64
	ds_read_b128 v[244:247], v176 offset:2624
	s_setprio 1
	s_waitcnt lgkmcnt(1)
	v_mfma_f32_16x16x32_bf16 v[60:63], v[240:243], v[198:201], v[60:63]
	v_mfma_f32_16x16x32_bf16 v[52:55], v[240:243], v[228:231], v[52:55]
	v_mfma_f32_16x16x32_bf16 v[48:51], v[240:243], v[232:235], v[48:51]
	v_mfma_f32_16x16x32_bf16 v[56:59], v[240:243], v[236:239], v[56:59]
	s_waitcnt lgkmcnt(0)
	v_mfma_f32_16x16x32_bf16 v[40:43], v[244:247], v[198:201], v[40:43]
	v_mfma_f32_16x16x32_bf16 v[36:39], v[244:247], v[228:231], v[36:39]
	v_mfma_f32_16x16x32_bf16 v[32:35], v[244:247], v[232:235], v[32:35]
	v_mfma_f32_16x16x32_bf16 v[44:47], v[244:247], v[236:239], v[44:47]
	s_setprio 0
	ds_read_b128 v[240:243], v176 offset:5184
	ds_read_b128 v[244:247], v176 offset:7744
	s_andn2_b64 vcc, exec, s[10:11]
	s_cbranch_vccnz .Lmy_il_last_795
	s_bitcmp1_b32 s22, 0
	s_cselect_b32 s10, 0xf000, 0
	s_setprio 1
	s_waitcnt lgkmcnt(1)
	v_mfma_f32_16x16x32_bf16 v[28:31], v[240:243], v[198:201], v[28:31]
	v_mfma_f32_16x16x32_bf16 v[20:23], v[240:243], v[228:231], v[20:23]
	v_add_u32_e32 v176, s10, v225
	s_waitcnt vmcnt(5)
	ds_write_b128 v176, v[64:67]
	v_mfma_f32_16x16x32_bf16 v[16:19], v[240:243], v[232:235], v[16:19]
	s_waitcnt vmcnt(4)
	ds_write_b128 v176, v[68:71] offset:10240
	v_mfma_f32_16x16x32_bf16 v[24:27], v[240:243], v[236:239], v[24:27]
	s_waitcnt vmcnt(3)
	ds_write_b128 v176, v[72:75] offset:20480
	s_waitcnt lgkmcnt(3)
	v_mfma_f32_16x16x32_bf16 v[8:11], v[244:247], v[198:201], v[8:11]
	s_waitcnt vmcnt(2)
	ds_write_b128 v176, v[76:79] offset:30720
	v_mfma_f32_16x16x32_bf16 v[4:7], v[244:247], v[228:231], v[4:7]
	s_waitcnt vmcnt(1)
	ds_write_b128 v176, v[80:83] offset:40960
	v_mfma_f32_16x16x32_bf16 v[0:3], v[244:247], v[232:235], v[0:3]
	s_waitcnt vmcnt(0)
	ds_write_b128 v176, v[84:87] offset:51200
	v_mfma_f32_16x16x32_bf16 v[12:15], v[244:247], v[236:239], v[12:15]
	s_setprio 0
	s_branch .LBB0_795
.Lmy_il_last_795:
	s_setprio 1
	s_waitcnt lgkmcnt(1)
	v_mfma_f32_16x16x32_bf16 v[28:31], v[240:243], v[198:201], v[28:31]
	v_mfma_f32_16x16x32_bf16 v[20:23], v[240:243], v[228:231], v[20:23]
	v_mfma_f32_16x16x32_bf16 v[16:19], v[240:243], v[232:235], v[16:19]
	v_mfma_f32_16x16x32_bf16 v[24:27], v[240:243], v[236:239], v[24:27]
	s_waitcnt lgkmcnt(0)
	v_mfma_f32_16x16x32_bf16 v[8:11], v[244:247], v[198:201], v[8:11]
	v_mfma_f32_16x16x32_bf16 v[4:7], v[244:247], v[228:231], v[4:7]
	v_mfma_f32_16x16x32_bf16 v[0:3], v[244:247], v[232:235], v[0:3]
	v_mfma_f32_16x16x32_bf16 v[12:15], v[244:247], v[236:239], v[12:15]
	s_setprio 0
	s_branch .LBB0_795

; __device__ __forceinline__ f32x4 mfma16(bf16x8 a, bf16x8 b, f32x4 c) { return __builtin_amdgcn_mfma_f32_16x16x32_bf16(a, b, c, 0, 0, 0); }
; template <int NT, bool LOWREG = false>
; __device__ __forceinline__ void gemm_mainloop(const bh* __restrict__ A, long lda, const bh* __restrict__ B, long ldb, int K,
;                                               char* lds, f32x4 (&acc)[4][NT]) {
;     ...
;     const char* sb = lds + (kt & 1) * STAGE;
;     const char* a_base = sb + (wr * 64 + fr) * LROW + fq * 16;
;     const char* b_base = sb + A_BYTES + (wc * (16 * NT) + fr) * LROW + fq * 16;
; #pragma unroll
;     for (int ks = 0; ks < 2; ++ks) {
;       if constexpr (LOWREG) {
;         bf16x8 bfr[NT];
; #pragma unroll
;         for (int n = 0; n < NT; ++n) bfr[n] = *reinterpret_cast<const bf16x8*>(b_base + n * 16 * LROW + ks * 64);
; #pragma unroll
;         for (int mp = 0; mp < 2; ++mp) {
;           bf16x8 af[2];
; #pragma unroll
;           for (int m = 0; m < 2; ++m) af[m] = *reinterpret_cast<const bf16x8*>(a_base + (mp * 2 + m) * 16 * LROW + ks * 64);
;           __builtin_amdgcn_s_setprio(1);
; #pragma unroll
;           for (int m = 0; m < 2; ++m)
; #pragma unroll
;             for (int n = 0; n < NT; ++n) acc[mp * 2 + m][n] = mfma16(af[m], bfr[n], acc[mp * 2 + m][n]);
;           __builtin_amdgcn_s_setprio(0);
;         }
;       } else {
;       bf16x8 af[4], bfr[NT];
; #pragma unroll
;       for (int m = 0; m < 4; ++m) af[m] = *reinterpret_cast<const bf16x8*>(a_base + m * 16 * LROW + ks * 64);
; #pragma unroll
;       for (int n = 0; n < NT; ++n) bfr[n] = *reinterpret_cast<const bf16x8*>(b_base + n * 16 * LROW + ks * 64);
;       __builtin_amdgcn_s_setprio(1);
; #pragma unroll
;       for (int m = 0; m < 4; ++m)
; #pragma unroll
;         for (int n = 0; n < NT; ++n) acc[m][n] = mfma16(af[m], bfr[n], acc[m][n]);
;       __builtin_amdgcn_s_setprio(0);
;       }
;     }
;     if (more) {
;       char* wb = lds + ((kt + 1) & 1) * STAGE;
; #pragma unroll
;       for (int i = 0; i < 4; ++i) *reinterpret_cast<bf16x8*>(wb + (srow + 64 * i) * LROW + scol * 2) = ra[i];
; #pragma unroll
;       for (int i = 0; i < NB; ++i) *reinterpret_cast<bf16x8*>(wb + A_BYTES + (srow + 64 * i) * LROW + scol * 2) = rb[i];
;     }
;     __syncthreads();
.LBB0_935:
	s_add_i32 s5, s3, 1
	s_bitcmp1_b32 s3, 0
	s_cselect_b32 s3, 0xc800, 0
	s_add_i32 s3, s3, 32
	v_add3_u32 v86, s3, v60, v58
	v_add3_u32 v87, s3, v61, v58
	ds_read_b128 v[62:65], v86
	ds_read_b128 v[66:69], v86 offset:2560
	ds_read_b128 v[70:73], v86 offset:5120
	ds_read_b128 v[74:77], v86 offset:7680
	ds_read_b128 v[78:81], v87 offset:40960
	ds_read_b128 v[82:85], v87 offset:43520
	s_setprio 1
	s_waitcnt lgkmcnt(1)
	v_mfma_f32_16x16x32_bf16 v[48:51], v[62:65], v[78:81], v[48:51]
	s_waitcnt lgkmcnt(0)
	v_mfma_f32_16x16x32_bf16 v[44:47], v[62:65], v[82:85], v[44:47]
	v_mfma_f32_16x16x32_bf16 v[32:35], v[66:69], v[78:81], v[32:35]
	v_mfma_f32_16x16x32_bf16 v[16:19], v[66:69], v[82:85], v[16:19]
	v_mfma_f32_16x16x32_bf16 v[12:15], v[70:73], v[78:81], v[12:15]
	v_mfma_f32_16x16x32_bf16 v[8:11], v[70:73], v[82:85], v[8:11]
	v_mfma_f32_16x16x32_bf16 v[4:7], v[74:77], v[78:81], v[4:7]
	v_mfma_f32_16x16x32_bf16 v[0:3], v[74:77], v[82:85], v[0:3]
	s_setprio 0
	ds_read_b128 v[62:65], v86 offset:64
	ds_read_b128 v[66:69], v86 offset:2624
	ds_read_b128 v[70:73], v86 offset:5184
	ds_read_b128 v[74:77], v86 offset:7744
	ds_read_b128 v[78:81], v87 offset:41024
	ds_read_b128 v[82:85], v87 offset:43584
	s_andn2_b64 vcc, exec, s[14:15]
	s_cbranch_vccnz .Lmy_il_last_932
	s_bitcmp1_b32 s5, 0
	s_cselect_b32 s3, 0xc800, 0
	s_add_i32 s3, s3, 32
	s_setprio 1
	s_waitcnt lgkmcnt(1)
	v_mfma_f32_16x16x32_bf16 v[48:51], v[62:65], v[78:81], v[48:51]
	s_waitcnt lgkmcnt(0)
	v_mfma_f32_16x16x32_bf16 v[44:47], v[62:65], v[82:85], v[44:47]
	v_mfma_f32_16x16x32_bf16 v[32:35], v[66:69], v[78:81], v[32:35]
	v_add3_u32 v62, s3, v176, v59
	s_waitcnt vmcnt(4)
	ds_write_b128 v62, v[20:23]
	v_mfma_f32_16x16x32_bf16 v[16:19], v[66:69], v[82:85], v[16:19]
	s_waitcnt vmcnt(3)
	ds_write_b128 v62, v[24:27] offset:10240
	v_mfma_f32_16x16x32_bf16 v[12:15], v[70:73], v[78:81], v[12:15]
	s_waitcnt vmcnt(2)
	ds_write_b128 v62, v[28:31] offset:20480
	v_mfma_f32_16x16x32_bf16 v[8:11], v[70:73], v[82:85], v[8:11]
	s_waitcnt vmcnt(1)
	ds_write_b128 v62, v[36:39] offset:30720
	v_mfma_f32_16x16x32_bf16 v[4:7], v[74:77], v[78:81], v[4:7]
	v_add3_u32 v62, s3, v59, v176
	s_waitcnt vmcnt(0)
	ds_write_b128 v62, v[40:43] offset:40960
	v_mfma_f32_16x16x32_bf16 v[0:3], v[74:77], v[82:85], v[0:3]
	s_setprio 0
	s_branch .LBB0_932
.Lmy_il_last_932:
	s_setprio 1
	s_waitcnt lgkmcnt(1)
	v_mfma_f32_16x16x32_bf16 v[48:51], v[62:65], v[78:81], v[48:51]
	s_waitcnt lgkmcnt(0)
	v_mfma_f32_16x16x32_bf16 v[44:47], v[62:65], v[82:85], v[44:47]
	v_mfma_f32_16x16x32_bf16 v[32:35], v[66:69], v[78:81], v[32:35]
	v_mfma_f32_16x16x32_bf16 v[16:19], v[66:69], v[82:85], v[16:19]
	v_mfma_f32_16x16x32_bf16 v[12:15], v[70:73], v[78:81], v[12:15]
	v_mfma_f32_16x16x32_bf16 v[8:11], v[70:73], v[82:85], v[8:11]
	v_mfma_f32_16x16x32_bf16 v[4:7], v[74:77], v[78:81], v[4:7]
	v_mfma_f32_16x16x32_bf16 v[0:3], v[74:77], v[82:85], v[0:3]
	s_setprio 0
	s_branch .LBB0_932

; __device__ __forceinline__ f32x4 mfma16(bf16x8 a, bf16x8 b, f32x4 c) { return __builtin_amdgcn_mfma_f32_16x16x32_bf16(a, b, c, 0, 0, 0); }
; template <int NT, bool LOWREG = false>
; __device__ __forceinline__ void gemm_mainloop(const bh* __restrict__ A, long lda, const bh* __restrict__ B, long ldb, int K,
;                                               char* lds, f32x4 (&acc)[4][NT]) {
;     ...
;     const char* sb = lds + (kt & 1) * STAGE;
;     const char* a_base = sb + (wr * 64 + fr) * LROW + fq * 16;
;     const char* b_base = sb + A_BYTES + (wc * (16 * NT) + fr) * LROW + fq * 16;
; #pragma unroll
;     for (int ks = 0; ks < 2; ++ks) {
;       if constexpr (LOWREG) {
;         bf16x8 bfr[NT];
; #pragma unroll
;         for (int n = 0; n < NT; ++n) bfr[n] = *reinterpret_cast<const bf16x8*>(b_base + n * 16 * LROW + ks * 64);
; #pragma unroll
;         for (int mp = 0; mp < 2; ++mp) {
;           bf16x8 af[2];
; #pragma unroll
;           for (int m = 0; m < 2; ++m) af[m] = *reinterpret_cast<const bf16x8*>(a_base + (mp * 2 + m) * 16 * LROW + ks * 64);
;           __builtin_amdgcn_s_setprio(1);
; #pragma unroll
;           for (int m = 0; m < 2; ++m)
; #pragma unroll
;             for (int n = 0; n < NT; ++n) acc[mp * 2 + m][n] = mfma16(af[m], bfr[n], acc[mp * 2 + m][n]);
;           __builtin_amdgcn_s_setprio(0);
;         }
;       } else {
;       bf16x8 af[4], bfr[NT];
; #pragma unroll
;       for (int m = 0; m < 4; ++m) af[m] = *reinterpret_cast<const bf16x8*>(a_base + m * 16 * LROW + ks * 64);
; #pragma unroll
;       for (int n = 0; n < NT; ++n) bfr[n] = *reinterpret_cast<const bf16x8*>(b_base + n * 16 * LROW + ks * 64);
;       __builtin_amdgcn_s_setprio(1);
; #pragma unroll
;       for (int m = 0; m < 4; ++m)
; #pragma unroll
;         for (int n = 0; n < NT; ++n) acc[m][n] = mfma16(af[m], bfr[n], acc[m][n]);
;       __builtin_amdgcn_s_setprio(0);
;       }
;     }
;     if (more) {
;       char* wb = lds + ((kt + 1) & 1) * STAGE;
; #pragma unroll
;       for (int i = 0; i < 4; ++i) *reinterpret_cast<bf16x8*>(wb + (srow + 64 * i) * LROW + scol * 2) = ra[i];
; #pragma unroll
;       for (int i = 0; i < NB; ++i) *reinterpret_cast<bf16x8*>(wb + A_BYTES + (srow + 64 * i) * LROW + scol * 2) = rb[i];
;     }
;     __syncthreads();
.LBB0_1134:
	s_add_i32 s5, s3, 1
	s_bitcmp1_b32 s3, 0
	s_cselect_b32 s3, 0xf000, 0
	s_add_i32 s3, s3, 32
	v_add3_u32 v97, s3, v95, v93
	v_add3_u32 v130, s3, v96, v93
	ds_read_b128 v[98:101], v97
	ds_read_b128 v[102:105], v97 offset:2560
	ds_read_b128 v[106:109], v97 offset:5120
	ds_read_b128 v[110:113], v97 offset:7680
	ds_read_b128 v[114:117], v130 offset:40960
	ds_read_b128 v[118:121], v130 offset:43520
	ds_read_b128 v[122:125], v130 offset:46080
	ds_read_b128 v[126:129], v130 offset:48640
	s_setprio 1
	s_waitcnt lgkmcnt(3)
	v_mfma_f32_16x16x32_bf16 v[84:87], v[98:101], v[114:117], v[84:87]
	s_waitcnt lgkmcnt(2)
	v_mfma_f32_16x16x32_bf16 v[80:83], v[98:101], v[118:121], v[80:83]
	s_waitcnt lgkmcnt(1)
	v_mfma_f32_16x16x32_bf16 v[76:79], v[98:101], v[122:125], v[76:79]
	s_waitcnt lgkmcnt(0)
	v_mfma_f32_16x16x32_bf16 v[72:75], v[98:101], v[126:129], v[72:75]
	v_mfma_f32_16x16x32_bf16 v[68:71], v[102:105], v[114:117], v[68:71]
	v_mfma_f32_16x16x32_bf16 v[64:67], v[102:105], v[118:121], v[64:67]
	v_mfma_f32_16x16x32_bf16 v[60:63], v[102:105], v[122:125], v[60:63]
	v_mfma_f32_16x16x32_bf16 v[56:59], v[102:105], v[126:129], v[56:59]
	v_mfma_f32_16x16x32_bf16 v[52:55], v[106:109], v[114:117], v[52:55]
	v_mfma_f32_16x16x32_bf16 v[48:51], v[106:109], v[118:121], v[48:51]
	v_mfma_f32_16x16x32_bf16 v[44:47], v[106:109], v[122:125], v[44:47]
	v_mfma_f32_16x16x32_bf16 v[40:43], v[106:109], v[126:129], v[40:43]
	v_mfma_f32_16x16x32_bf16 v[36:39], v[110:113], v[114:117], v[36:39]
	v_mfma_f32_16x16x32_bf16 v[28:31], v[110:113], v[118:121], v[28:31]
	v_mfma_f32_16x16x32_bf16 v[20:23], v[110:113], v[122:125], v[20:23]
	v_mfma_f32_16x16x32_bf16 v[8:11], v[110:113], v[126:129], v[8:11]
	s_setprio 0
	ds_read_b128 v[98:101], v97 offset:64
	ds_read_b128 v[102:105], v97 offset:2624
	ds_read_b128 v[106:109], v97 offset:5184
	ds_read_b128 v[110:113], v97 offset:7744
	ds_read_b128 v[114:117], v130 offset:41024
	ds_read_b128 v[118:121], v130 offset:43584
	ds_read_b128 v[122:125], v130 offset:46144
	ds_read_b128 v[126:129], v130 offset:48704
	s_andn2_b64 vcc, exec, s[10:11]
	s_cbranch_vccnz .Lmy_il_last_1131
	s_bitcmp1_b32 s5, 0
	s_cselect_b32 s3, 0xf000, 0
	s_setprio 1
	s_waitcnt lgkmcnt(3)
	v_mfma_f32_16x16x32_bf16 v[84:87], v[98:101], v[114:117], v[84:87]
	s_waitcnt lgkmcnt(2)
	v_mfma_f32_16x16x32_bf16 v[80:83], v[98:101], v[118:121], v[80:83]
	s_waitcnt lgkmcnt(1)
	v_mfma_f32_16x16x32_bf16 v[76:79], v[98:101], v[122:125], v[76:79]
	s_waitcnt lgkmcnt(0)
	v_mfma_f32_16x16x32_bf16 v[72:75], v[98:101], v[126:129], v[72:75]
	v_mfma_f32_16x16x32_bf16 v[68:71], v[102:105], v[114:117], v[68:71]
	v_add_u32_e32 v97, s3, v94
	s_waitcnt vmcnt(5)
	ds_write_b128 v97, v[0:3]
	v_mfma_f32_16x16x32_bf16 v[64:67], v[102:105], v[118:121], v[64:67]
	v_mfma_f32_16x16x32_bf16 v[60:63], v[102:105], v[122:125], v[60:63]
	s_waitcnt vmcnt(4)
	ds_write_b128 v97, v[4:7] offset:10240
	v_mfma_f32_16x16x32_bf16 v[56:59], v[102:105], v[126:129], v[56:59]
	v_mfma_f32_16x16x32_bf16 v[52:55], v[106:109], v[114:117], v[52:55]
	s_waitcnt vmcnt(3)
	ds_write_b128 v97, v[12:15] offset:20480
	v_mfma_f32_16x16x32_bf16 v[48:51], v[106:109], v[118:121], v[48:51]
	v_mfma_f32_16x16x32_bf16 v[44:47], v[106:109], v[122:125], v[44:47]
	s_waitcnt vmcnt(2)
	ds_write_b128 v97, v[16:19] offset:30720
	v_mfma_f32_16x16x32_bf16 v[40:43], v[106:109], v[126:129], v[40:43]
	v_mfma_f32_16x16x32_bf16 v[36:39], v[110:113], v[114:117], v[36:39]
	s_waitcnt vmcnt(1)
	ds_write_b128 v97, v[24:27] offset:40960
	v_mfma_f32_16x16x32_bf16 v[28:31], v[110:113], v[118:121], v[28:31]
	v_mfma_f32_16x16x32_bf16 v[20:23], v[110:113], v[122:125], v[20:23]
	s_waitcnt vmcnt(0)
	ds_write_b128 v97, v[32:35] offset:51200
	v_mfma_f32_16x16x32_bf16 v[8:11], v[110:113], v[126:129], v[8:11]
	s_setprio 0
	s_branch .LBB0_1131
